# baseline (speedup 1.0000x reference)
; template <bool SB>
; DEV void attn_pass(const bf16_t* __restrict__ proj, int qcol, int kcol, int vcol, int q0, f32x16 (&o)[4], float& l_out, unsigned char* lds) {
;     ...
;     if (j <= jw) {
;       const unsigned char* Ks = K_lds + buf * 16384;
;       f32x16 p0 = {}, p1 = {};
; #pragma unroll
;       for (int d0 = 0; d0 < NDK; ++d0) { const int cb = ((d0 * 16 + hi * 8) * 2) ^ ((r32 & 7) << 4);
;         bf16x8 b0 = *reinterpret_cast<const bf16x8*>(Ks + r32 * KROWB + cb);
;         bf16x8 b1 = *reinterpret_cast<const bf16x8*>(Ks + (32 + r32) * KROWB + cb);
;         p0 = __builtin_amdgcn_mfma_f32_32x32x16_bf16(b0, qr[d0], p0, 0, 0, 0);
;         p1 = __builtin_amdgcn_mfma_f32_32x32x16_bf16(b1, qr[d0], p1, 0, 0, 0); }
;       bf16x8 pa0, pa1, pa2, pa3;
;       if constexpr (SB) {
;         const bool diag = (j == jw); const int rl = 32 * (wid & 1) + r32;
;         float T[8], Pg[8];
.LBB0_356:
	s_and_b32 s83, s79, 1
	v_cmp_le_i32_e32 vcc, s84, v208
	v_mov_b32_e32 v64, 0
	s_and_saveexec_b64 s[94:95], vcc
	s_cbranch_execz .LBB0_363
	s_lshl_b32 s90, s83, 14
	v_add_u32_e32 v156, s90, v223
	v_add_u32_e32 v68, v156, v224
	ds_read_b128 v[64:67], v68 offset:32768
	ds_read_b128 v[68:71], v68 offset:40960
	v_add_u32_e32 v152, v156, v225
	ds_read_b128 v[148:151], v152 offset:32768
	ds_read_b128 v[152:155], v152 offset:40960
	v_cmp_ne_u32_e32 vcc, s79, v233
	s_waitcnt lgkmcnt(3)
	v_mfma_f32_32x32x16_bf16 v[80:95], v[64:67], v[112:115], 0
	s_waitcnt lgkmcnt(2)
	v_mfma_f32_32x32x16_bf16 v[64:79], v[68:71], v[112:115], 0
	s_waitcnt lgkmcnt(1)
	v_mfma_f32_32x32x16_bf16 v[80:95], v[148:151], v[116:119], v[80:95]
	s_waitcnt lgkmcnt(0)
	v_mfma_f32_32x32x16_bf16 v[64:79], v[152:155], v[116:119], v[64:79]
	v_add_u32_e32 v152, v156, v226
	ds_read_b128 v[148:151], v152 offset:32768
	ds_read_b128 v[152:155], v152 offset:40960
	s_waitcnt lgkmcnt(1)
	v_mfma_f32_32x32x16_bf16 v[80:95], v[148:151], v[120:123], v[80:95]
	s_waitcnt lgkmcnt(0)
	v_mfma_f32_32x32x16_bf16 v[64:79], v[152:155], v[120:123], v[64:79]
	v_add_u32_e32 v152, v156, v227
	ds_read_b128 v[148:151], v152 offset:32768
	ds_read_b128 v[152:155], v152 offset:40960
	s_waitcnt lgkmcnt(1)
	v_mfma_f32_32x32x16_bf16 v[80:95], v[148:151], v[124:127], v[80:95]
	s_waitcnt lgkmcnt(0)
	v_mfma_f32_32x32x16_bf16 v[64:79], v[152:155], v[124:127], v[64:79]
	v_add_u32_e32 v152, v156, v228
	ds_read_b128 v[148:151], v152 offset:32768
	ds_read_b128 v[152:155], v152 offset:40960
	s_waitcnt lgkmcnt(1)
	v_mfma_f32_32x32x16_bf16 v[80:95], v[148:151], v[128:131], v[80:95]
	s_waitcnt lgkmcnt(0)
	v_mfma_f32_32x32x16_bf16 v[64:79], v[152:155], v[128:131], v[64:79]
	v_add_u32_e32 v152, v156, v229
	ds_read_b128 v[148:151], v152 offset:32768
	ds_read_b128 v[152:155], v152 offset:40960
	s_waitcnt lgkmcnt(1)
	v_mfma_f32_32x32x16_bf16 v[80:95], v[148:151], v[132:135], v[80:95]
	s_waitcnt lgkmcnt(0)
	v_mfma_f32_32x32x16_bf16 v[64:79], v[152:155], v[132:135], v[64:79]
	v_add_u32_e32 v152, v156, v230
	ds_read_b128 v[148:151], v152 offset:32768
	ds_read_b128 v[152:155], v152 offset:40960
	s_waitcnt lgkmcnt(1)
	v_mfma_f32_32x32x16_bf16 v[80:95], v[148:151], v[136:139], v[80:95]
	s_waitcnt lgkmcnt(0)
	v_mfma_f32_32x32x16_bf16 v[64:79], v[152:155], v[136:139], v[64:79]
	v_add_u32_e32 v152, v156, v231
	ds_read_b128 v[148:151], v152 offset:32768
	ds_read_b128 v[152:155], v152 offset:40960
	s_waitcnt lgkmcnt(1)
	v_mfma_f32_32x32x16_bf16 v[80:95], v[148:151], v[140:143], v[80:95]
	s_waitcnt lgkmcnt(0)
	v_mfma_f32_32x32x16_bf16 v[64:79], v[152:155], v[140:143], v[64:79]
	s_nop 9
	v_min_f32_e32 v80, 0x42a00000, v80
	v_exp_f32_e32 v80, v80
	s_nop 0
	v_add_f32_e32 v148, 1.0, v80
	v_rcp_f32_e32 v244, v148
	s_nop 0
	v_mul_f32_e32 v186, v80, v244
	s_and_saveexec_b64 s[96:97], vcc
	s_xor_b64 vcc, exec, s[96:97]
	s_cbranch_execz .LBB0_359
	v_min_f32_e32 v80, 0x42a00000, v81
	v_exp_f32_e32 v81, v80
	v_min_f32_e32 v80, 0x42a00000, v82
	v_exp_f32_e32 v80, v80
	v_min_f32_e32 v82, 0x42a00000, v83
	v_exp_f32_e32 v83, v82
	v_add_f32_e32 v82, 1.0, v81
	v_add_f32_e32 v148, 1.0, v80
	v_rcp_f32_e32 v149, v148
	v_add_f32_e32 v148, 1.0, v83
	v_rcp_f32_e32 v148, v148
	v_rcp_f32_e32 v150, v82
	v_mul_f32_e32 v82, v80, v149
	v_max_f32_e32 v66, v66, v66
	v_mul_f32_e32 v80, v148, v149
	v_pk_mul_f32 v[150:151], v[150:151], v[80:81] op_sel_hi:[0,1]
	v_mov_b32_e32 v187, v80
	v_min_f32_e32 v80, 0x42a00000, v84
	v_exp_f32_e32 v80, v80
	v_pk_mul_f32 v[148:149], v[148:149], v[82:83] op_sel_hi:[0,1]
	v_min_f32_e32 v83, 0x42a00000, v86
	v_add_f32_e32 v81, 1.0, v80
	v_rcp_f32_e32 v84, v81
	v_max_f32_e32 v81, v85, v85
	v_exp_f32_e32 v83, v83
	v_min_f32_e32 v85, 0x42a00000, v87
	v_exp_f32_e32 v87, v85
	v_min_f32_e32 v81, 0x42a00000, v81
	v_exp_f32_e32 v153, v81
	v_add_f32_e32 v81, 1.0, v83
	v_rcp_f32_e32 v85, v81
	v_add_f32_e32 v81, 1.0, v87
	v_rcp_f32_e32 v81, v81
	v_add_f32_e32 v86, 1.0, v153
	v_rcp_f32_e32 v154, v86
	v_mul_f32_e32 v86, v83, v85
	v_pk_mul_f32 v[158:159], v[80:81], v[84:85]
	v_mov_b32_e32 v80, v81
	v_mov_b32_e32 v152, v159
	v_pk_mul_f32 v[152:153], v[154:155], v[152:153] op_sel_hi:[0,1]
	v_mul_f32_e32 v156, v244, v150
	v_mul_f32_e32 v157, v84, v152
	v_pk_mul_f32 v[154:155], v[152:153], v[158:159]
	v_pk_mul_f32 v[152:153], v[80:81], v[86:87] op_sel_hi:[0,1]
	v_mov_b32_e32 v82, v156
	v_mov_b32_e32 v83, v157
	v_min_f32_e32 v80, 0x42a00000, v88
	v_permlane32_swap_b32_e32 v156, v82
	v_permlane32_swap_b32_e32 v157, v83
	v_exp_f32_e32 v80, v80
	v_pk_mul_f32 v[156:157], v[156:157], v[82:83]
	v_cndmask_b32_e64 v235, 1.0, v83, s[4:5]
	v_min_f32_e32 v83, 0x42a00000, v90
	v_exp_f32_e32 v84, v83
	v_add_f32_e32 v81, 1.0, v80
	v_min_f32_e32 v83, 0x42a00000, v91
	v_pk_mul_f32 v[150:151], v[186:187], v[150:151]
	v_cndmask_b32_e64 v187, 1.0, v82, s[4:5]
	v_rcp_f32_e32 v82, v81
	v_exp_f32_e32 v85, v83
	v_min_f32_e32 v81, 0x42a00000, v89
	v_exp_f32_e32 v87, v81
	v_add_f32_e32 v81, 1.0, v84
	v_rcp_f32_e32 v83, v81
	v_add_f32_e32 v81, 1.0, v85
	v_rcp_f32_e32 v81, v81
	v_add_f32_e32 v86, 1.0, v87
	v_rcp_f32_e32 v88, v86
	v_mul_f32_e32 v84, v84, v83
	v_pk_mul_f32 v[90:91], v[80:81], v[82:83]
	v_mov_b32_e32 v86, v91
	v_pk_mul_f32 v[86:87], v[88:89], v[86:87] op_sel_hi:[0,1]
	v_mul_f32_e32 v80, v82, v86
	v_mov_b32_e32 v82, v81
	v_min_f32_e32 v81, 0x42a00000, v92
	v_pk_mul_f32 v[158:159], v[82:83], v[84:85] op_sel_hi:[0,1]
	v_exp_f32_e32 v82, v81
	v_min_f32_e32 v83, 0x42a00000, v94
	v_exp_f32_e32 v85, v83
	v_add_f32_e32 v81, 1.0, v82
	v_min_f32_e32 v83, 0x42a00000, v95
	v_pk_mul_f32 v[160:161], v[86:87], v[90:91]
	v_rcp_f32_e32 v86, v81
	v_exp_f32_e32 v89, v83
; template <bool SB>
; DEV void attn_pass(const bf16_t* __restrict__ proj, int qcol, int kcol, int vcol, int q0, f32x16 (&o)[4], float& l_out, unsigned char* lds) {
;     ...
;         if (diag) {
;           SBGRP(p0, 0, 0); SBGRP(p0, 1, 0); SBGRP(p0, 2, 0); SBGRP(p0, 3, 0);
;           SBGRP(p1, 0, 32); SBGRP(p1, 1, 32); SBGRP(p1, 2, 32); SBGRP(p1, 3, 32);
;         } else {
;           SBGRPF(p0, 0, 0); SBGRPF(p0, 1, 0); SBGRPF(p0, 2, 0); SBGRPF(p0, 3, 0);
;           SBGRPF(p1, 0, 32); SBGRPF(p1, 1, 32); SBGRPF(p1, 2, 32); SBGRPF(p1, 3, 32);
	v_min_f32_e32 v81, 0x42a00000, v93
	v_exp_f32_e32 v91, v81
	v_add_f32_e32 v81, 1.0, v85
	v_rcp_f32_e32 v87, v81
	v_add_f32_e32 v81, 1.0, v89
	v_rcp_f32_e32 v83, v81
	v_add_f32_e32 v81, 1.0, v91
	v_rcp_f32_e32 v92, v81
	v_min_f32_e32 v66, 0x42a00000, v66
	v_pk_mul_f32 v[94:95], v[82:83], v[86:87]
	v_mov_b32_e32 v90, v95
	v_min_f32_e32 v64, 0x42a00000, v64
	v_exp_f32_e32 v66, v66
	v_min_f32_e32 v67, 0x42a00000, v67
	v_pk_mul_f32 v[90:91], v[92:93], v[90:91] op_sel_hi:[0,1]
	v_exp_f32_e32 v64, v64
	v_exp_f32_e32 v67, v67
	v_mul_f32_e32 v88, v85, v87
	v_mul_f32_e32 v81, v86, v90
	v_mov_b32_e32 v82, v83
	v_min_f32_e32 v65, 0x42a00000, v65
	v_mov_b32_e32 v84, v80
	v_pk_mul_f32 v[164:165], v[82:83], v[88:89] op_sel_hi:[0,1]
	v_mov_b32_e32 v85, v81
	v_exp_f32_e32 v83, v65
	v_permlane32_swap_b32_e32 v80, v84
	v_permlane32_swap_b32_e32 v81, v85
	v_add_f32_e32 v65, 1.0, v66
	v_pk_mul_f32 v[166:167], v[80:81], v[84:85]
	v_add_f32_e32 v80, 1.0, v64
	v_rcp_f32_e32 v81, v65
	v_add_f32_e32 v65, 1.0, v67
	v_rcp_f32_e32 v80, v80
	v_rcp_f32_e32 v65, v65
	v_add_f32_e32 v82, 1.0, v83
	v_cndmask_b32_e64 v236, 1.0, v84, s[4:5]
	v_rcp_f32_e32 v84, v82
	v_pk_mul_f32 v[86:87], v[64:65], v[80:81]
	v_mul_f32_e32 v66, v66, v81
	v_mov_b32_e32 v82, v87
	v_pk_mul_f32 v[82:83], v[84:85], v[82:83] op_sel_hi:[0,1]
	v_mul_f32_e32 v64, v80, v82
	v_mov_b32_e32 v80, v65
	v_min_f32_e32 v65, 0x42a00000, v68
	v_pk_mul_f32 v[168:169], v[80:81], v[66:67] op_sel_hi:[0,1]
	v_exp_f32_e32 v66, v65
	v_min_f32_e32 v67, 0x42a00000, v70
	v_pk_mul_f32 v[170:171], v[82:83], v[86:87]
	v_add_f32_e32 v65, 1.0, v66
	v_rcp_f32_e32 v80, v65
	v_max_f32_e32 v65, v69, v69
	v_exp_f32_e32 v69, v67
	v_min_f32_e32 v67, 0x42a00000, v71
	v_exp_f32_e32 v71, v67
	v_min_f32_e32 v65, 0x42a00000, v65
	v_exp_f32_e32 v83, v65
	v_add_f32_e32 v65, 1.0, v69
	v_rcp_f32_e32 v81, v65
	v_add_f32_e32 v65, 1.0, v71
	v_rcp_f32_e32 v67, v65
	v_add_f32_e32 v65, 1.0, v83
	v_rcp_f32_e32 v84, v65
	v_mul_f32_e32 v70, v69, v81
	v_pk_mul_f32 v[86:87], v[66:67], v[80:81]
	v_mov_b32_e32 v66, v67
	v_mov_b32_e32 v82, v87
	v_pk_mul_f32 v[82:83], v[84:85], v[82:83] op_sel_hi:[0,1]
	v_mul_f32_e32 v65, v80, v82
	v_mov_b32_e32 v68, v64
	v_pk_mul_f32 v[172:173], v[66:67], v[70:71] op_sel_hi:[0,1]
	v_mov_b32_e32 v69, v65
	v_permlane32_swap_b32_e32 v64, v68
	v_permlane32_swap_b32_e32 v65, v69
	v_min_f32_e32 v67, 0x42a00000, v74
	v_cndmask_b32_e64 v238, 1.0, v68, s[4:5]
	v_pk_mul_f32 v[176:177], v[64:65], v[68:69]
	v_exp_f32_e32 v68, v67
	v_min_f32_e32 v66, 0x42a00000, v72
	v_min_f32_e32 v67, 0x42a00000, v75
	v_exp_f32_e32 v66, v66
	v_cndmask_b32_e64 v239, 1.0, v69, s[4:5]
	v_exp_f32_e32 v69, v67
	v_min_f32_e32 v65, 0x42a00000, v73
	v_exp_f32_e32 v71, v65
	v_add_f32_e32 v64, 1.0, v66
	v_add_f32_e32 v65, 1.0, v68
	v_add_f32_e32 v67, 1.0, v69
	v_rcp_f32_e32 v64, v64
	v_rcp_f32_e32 v65, v65
	v_rcp_f32_e32 v67, v67
	v_add_f32_e32 v70, 1.0, v71
	v_rcp_f32_e32 v72, v70
	v_mul_f32_e32 v68, v68, v65
	v_pk_mul_f32 v[74:75], v[66:67], v[64:65]
	v_pk_mul_f32 v[162:163], v[90:91], v[94:95]
	v_mov_b32_e32 v70, v75
	v_pk_mul_f32 v[70:71], v[72:73], v[70:71] op_sel_hi:[0,1]
	v_mul_f32_e32 v65, v64, v70
	v_mov_b32_e32 v64, v67
	v_pk_mul_f32 v[178:179], v[64:65], v[68:69] op_sel_hi:[0,1]
	v_min_f32_e32 v64, 0x42a00000, v76
	v_exp_f32_e32 v64, v64
	v_mov_b32_e32 v66, v65
	v_min_f32_e32 v67, 0x42a00000, v78
	s_nop 0
	v_permlane32_swap_b32_e32 v65, v66
	v_exp_f32_e32 v68, v67
	v_mul_f32_e32 v240, v65, v66
	v_add_f32_e32 v65, 1.0, v64
	v_min_f32_e32 v67, 0x42a00000, v79
	v_cndmask_b32_e64 v241, 1.0, v66, s[4:5]
	v_rcp_f32_e32 v66, v65
	v_exp_f32_e32 v69, v67
	v_min_f32_e32 v65, 0x42a00000, v77
	v_pk_mul_f32 v[180:181], v[70:71], v[74:75]
	v_exp_f32_e32 v71, v65
	v_add_f32_e32 v65, 1.0, v68
	v_rcp_f32_e32 v67, v65
	v_add_f32_e32 v65, 1.0, v69
	v_rcp_f32_e32 v65, v65
	v_add_f32_e32 v70, 1.0, v71
	v_rcp_f32_e32 v72, v70
	v_mul_f32_e32 v68, v68, v67
	v_pk_mul_f32 v[74:75], v[64:65], v[66:67]
	v_mov_b32_e32 v64, v65
	v_mov_b32_e32 v70, v75
	v_pk_mul_f32 v[70:71], v[72:73], v[70:71] op_sel_hi:[0,1]
	v_mul_f32_e32 v242, v66, v70
	v_mov_b32_e32 v243, v242
	v_cndmask_b32_e64 v237, 1.0, v85, s[4:5]
	v_pk_mul_f32 v[174:175], v[82:83], v[86:87]
	v_pk_mul_f32 v[184:185], v[70:71], v[74:75]
	v_pk_mul_f32 v[182:183], v[64:65], v[68:69] op_sel_hi:[0,1]
	v_permlane32_swap_b32_e32 v242, v243
; template <bool SB>
; DEV void attn_pass(const bf16_t* __restrict__ proj, int qcol, int kcol, int vcol, int q0, f32x16 (&o)[4], float& l_out, unsigned char* lds) {
;     ...
;         if (diag) {
;           SBGRP(p0, 0, 0); SBGRP(p0, 1, 0); SBGRP(p0, 2, 0); SBGRP(p0, 3, 0);
;           SBGRP(p1, 0, 32); SBGRP(p1, 1, 32); SBGRP(p1, 2, 32); SBGRP(p1, 3, 32);
.LBB0_359:
	s_andn2_saveexec_b64 vcc, vcc
	s_cbranch_execz .LBB0_361
	v_min_f32_e32 v80, 0x42a00000, v81
	v_exp_f32_e32 v80, v80
	v_min_f32_e32 v82, 0x42a00000, v82
	v_add_f32_e32 v149, 1.0, v80
	v_rcp_f32_e32 v149, v149
	v_exp_f32_e32 v82, v82
	v_cndmask_b32_e64 v81, 0, v186, s[8:9]
	v_cndmask_b32_e64 v148, 1.0, v244, s[8:9]
	v_mul_f32_e32 v80, v80, v149
	v_cndmask_b32_e64 v151, 0, v80, s[10:11]
	v_min_f32_e32 v80, 0x42a00000, v83
	v_exp_f32_e32 v80, v80
	v_add_f32_e32 v83, 1.0, v82
	v_cndmask_b32_e64 v150, 1.0, v149, s[10:11]
	v_rcp_f32_e32 v83, v83
	v_add_f32_e32 v149, 1.0, v80
	v_rcp_f32_e32 v152, v149
	v_max_f32_e32 v64, v64, v64
	v_mul_f32_e32 v82, v82, v83
	v_cndmask_b32_e64 v83, 1.0, v83, s[12:13]
	v_mul_f32_e32 v80, v80, v152
	v_cndmask_b32_e64 v152, 1.0, v152, s[14:15]
	v_mul_f32_e32 v83, v152, v83
	v_mul_f32_e32 v150, v150, v83
	v_cndmask_b32_e64 v149, 0, v80, s[14:15]
	v_mul_f32_e32 v80, v148, v150
	v_mul_f32_e32 v150, v81, v150
	v_min_f32_e32 v81, 0x42a00000, v84
	v_exp_f32_e32 v81, v81
	v_min_f32_e32 v84, 0x42a00000, v85
	v_exp_f32_e32 v84, v84
	v_mul_f32_e32 v151, v83, v151
	v_add_f32_e32 v83, 1.0, v81
	v_rcp_f32_e32 v83, v83
	v_add_f32_e32 v85, 1.0, v84
	v_rcp_f32_e32 v85, v85
	v_cndmask_b32_e64 v82, 0, v82, s[12:13]
	v_mul_f32_e32 v81, v81, v83
	v_mul_f32_e32 v148, v152, v82
	v_cndmask_b32_e64 v152, 0, v81, s[16:17]
	v_cndmask_b32_e64 v81, 1.0, v83, s[16:17]
	v_mul_f32_e32 v83, v84, v85
	v_max_f32_e32 v84, v86, v86
	v_min_f32_e32 v86, 0x42a00000, v87
	v_min_f32_e32 v84, 0x42a00000, v84
	v_exp_f32_e32 v86, v86
	v_exp_f32_e32 v84, v84
	v_cndmask_b32_e64 v85, 1.0, v85, s[18:19]
	v_cndmask_b32_e64 v83, 0, v83, s[18:19]
	v_add_f32_e32 v153, 1.0, v86
	v_add_f32_e32 v87, 1.0, v84
	v_rcp_f32_e32 v154, v153
	v_rcp_f32_e32 v87, v87
	v_mov_b32_e32 v82, v80
	s_nop 1
	v_permlane32_swap_b32_e32 v80, v82
	v_mul_f32_e32 v86, v86, v154
	v_mul_f32_e32 v84, v84, v87
	v_cndmask_b32_e64 v87, 1.0, v87, s[20:21]
	v_cndmask_b32_e64 v153, 0, v86, s[22:23]
	v_cndmask_b32_e64 v86, 1.0, v154, s[22:23]
	v_mul_f32_e32 v87, v86, v87
	v_mul_f32_e32 v85, v85, v87
	v_mul_f32_e32 v81, v81, v85
	v_mul_f32_e32 v155, v87, v83
	v_mov_b32_e32 v83, v81
	s_nop 1
	v_permlane32_swap_b32_e32 v81, v83
	v_pk_mul_f32 v[156:157], v[80:81], v[82:83]
	v_min_f32_e32 v80, 0x42a00000, v88
	v_exp_f32_e32 v80, v80
	v_cndmask_b32_e64 v187, 1.0, v82, s[4:5]
	v_cndmask_b32_e64 v84, 0, v84, s[20:21]
	v_mul_f32_e32 v154, v152, v85
	v_add_f32_e32 v82, 1.0, v80
	v_rcp_f32_e32 v82, v82
	v_mul_f32_e32 v152, v86, v84
	v_mul_f32_e32 v80, v80, v82
	v_cndmask_b32_e64 v84, 0, v80, s[24:25]
	v_cndmask_b32_e64 v80, 1.0, v82, s[24:25]
	v_min_f32_e32 v85, 0x42a00000, v91
	v_min_f32_e32 v81, 0x42a00000, v89
	v_min_f32_e32 v82, 0x42a00000, v90
	v_exp_f32_e32 v85, v85
	v_exp_f32_e32 v81, v81
	v_exp_f32_e32 v82, v82
	v_cndmask_b32_e64 v235, 1.0, v83, s[4:5]
	v_add_f32_e32 v87, 1.0, v85
	v_add_f32_e32 v83, 1.0, v81
	v_add_f32_e32 v86, 1.0, v82
	v_rcp_f32_e32 v87, v87
	v_rcp_f32_e32 v83, v83
	v_rcp_f32_e32 v86, v86
	v_min_f32_e32 v64, 0x42a00000, v64
	v_mul_f32_e32 v85, v85, v87
	v_mul_f32_e32 v81, v81, v83
	v_mul_f32_e32 v82, v82, v86
	v_cndmask_b32_e64 v86, 1.0, v86, s[28:29]
	v_cndmask_b32_e64 v159, 0, v85, s[30:31]
	v_cndmask_b32_e64 v85, 1.0, v87, s[30:31]
	v_cndmask_b32_e64 v81, 0, v81, s[26:27]
	v_cndmask_b32_e64 v83, 1.0, v83, s[26:27]
	v_mul_f32_e32 v86, v85, v86
	v_mul_f32_e32 v83, v83, v86
	v_mul_f32_e32 v161, v86, v81
	v_mul_f32_e32 v160, v84, v83
	v_min_f32_e32 v86, 0x42a00000, v94
	v_min_f32_e32 v87, 0x42a00000, v95
	v_mul_f32_e32 v80, v80, v83
	v_min_f32_e32 v84, 0x42a00000, v93
	v_exp_f32_e32 v86, v86
	v_exp_f32_e32 v87, v87
	v_min_f32_e32 v83, 0x42a00000, v92
	v_exp_f32_e32 v84, v84
	v_exp_f32_e32 v83, v83
	v_cndmask_b32_e64 v82, 0, v82, s[28:29]
	v_add_f32_e32 v88, 1.0, v86
	v_add_f32_e32 v89, 1.0, v87
	v_mul_f32_e32 v158, v85, v82
	v_add_f32_e32 v85, 1.0, v84
	v_rcp_f32_e32 v88, v88
	v_rcp_f32_e32 v89, v89
	v_add_f32_e32 v81, 1.0, v83
	v_rcp_f32_e32 v85, v85
	v_rcp_f32_e32 v81, v81
	v_mul_f32_e32 v86, v86, v88
	v_cndmask_b32_e64 v88, 1.0, v88, s[38:39]
	v_cndmask_b32_e64 v90, 1.0, v89, s[40:41]
	v_mul_f32_e32 v84, v84, v85
	v_cndmask_b32_e64 v85, 1.0, v85, s[36:37]
	v_mul_f32_e32 v88, v90, v88
	v_mul_f32_e32 v83, v83, v81
	v_cndmask_b32_e64 v81, 1.0, v81, s[34:35]
	v_mul_f32_e32 v85, v85, v88
	v_exp_f32_e32 v64, v64
	v_cndmask_b32_e64 v83, 0, v83, s[34:35]
	v_mul_f32_e32 v81, v81, v85
	v_mov_b32_e32 v82, v80
	v_mul_f32_e32 v162, v83, v85
	v_mov_b32_e32 v83, v81
	v_permlane32_swap_b32_e32 v80, v82
	s_nop 0
	v_permlane32_swap_b32_e32 v81, v83
	v_pk_mul_f32 v[166:167], v[80:81], v[82:83]
	v_add_f32_e32 v80, 1.0, v64
	v_rcp_f32_e32 v80, v80
	v_min_f32_e32 v66, 0x42a00000, v66
	v_min_f32_e32 v67, 0x42a00000, v67
	v_exp_f32_e32 v66, v66
	v_exp_f32_e32 v67, v67
	v_min_f32_e32 v65, 0x42a00000, v65
; template <bool SB>
; DEV void attn_pass(const bf16_t* __restrict__ proj, int qcol, int kcol, int vcol, int q0, f32x16 (&o)[4], float& l_out, unsigned char* lds) {
;     ...
;         if (diag) {
;           SBGRP(p0, 0, 0); SBGRP(p0, 1, 0); SBGRP(p0, 2, 0); SBGRP(p0, 3, 0);
;           SBGRP(p1, 0, 32); SBGRP(p1, 1, 32); SBGRP(p1, 2, 32); SBGRP(p1, 3, 32);
	v_mul_f32_e32 v64, v64, v80
	v_cndmask_b32_e64 v236, 1.0, v82, s[4:5]
	v_exp_f32_e32 v65, v65
	v_cndmask_b32_e64 v237, 1.0, v83, s[4:5]
	v_cndmask_b32_e64 v82, 0, v64, s[42:43]
	v_cndmask_b32_e64 v64, 1.0, v80, s[42:43]
	v_add_f32_e32 v80, 1.0, v66
	v_add_f32_e32 v83, 1.0, v67
	v_rcp_f32_e32 v80, v80
	v_rcp_f32_e32 v83, v83
	v_add_f32_e32 v81, 1.0, v65
	v_rcp_f32_e32 v81, v81
	v_mul_f32_e32 v66, v66, v80
	v_mul_f32_e32 v67, v67, v83
	v_cndmask_b32_e64 v66, 0, v66, s[46:47]
	v_cndmask_b32_e64 v80, 1.0, v80, s[46:47]
	v_cndmask_b32_e64 v169, 0, v67, s[48:49]
	v_cndmask_b32_e64 v67, 1.0, v83, s[48:49]
	v_min_f32_e32 v71, 0x42a00000, v71
	v_mul_f32_e32 v80, v67, v80
	v_mul_f32_e32 v168, v67, v66
	v_min_f32_e32 v70, 0x42a00000, v70
	v_exp_f32_e32 v71, v71
	v_min_f32_e32 v67, 0x42a00000, v69
	v_exp_f32_e32 v70, v70
	v_mul_f32_e32 v65, v65, v81
	v_cndmask_b32_e64 v81, 1.0, v81, s[44:45]
	v_min_f32_e32 v68, 0x42a00000, v68
	v_exp_f32_e32 v67, v67
	v_mul_f32_e32 v81, v81, v80
	v_exp_f32_e32 v68, v68
	v_cndmask_b32_e64 v65, 0, v65, s[44:45]
	v_mul_f32_e32 v64, v64, v81
	v_mul_f32_e32 v170, v82, v81
	v_add_f32_e32 v81, 1.0, v71
	v_mul_f32_e32 v171, v65, v80
	v_add_f32_e32 v80, 1.0, v70
	v_rcp_f32_e32 v81, v81
	v_add_f32_e32 v69, 1.0, v67
	v_rcp_f32_e32 v80, v80
	v_add_f32_e32 v65, 1.0, v68
	v_rcp_f32_e32 v69, v69
	v_rcp_f32_e32 v65, v65
	v_mul_f32_e32 v71, v71, v81
	v_mul_f32_e32 v70, v70, v80
	v_cndmask_b32_e64 v80, 1.0, v80, s[54:55]
	v_cndmask_b32_e64 v173, 0, v71, s[56:57]
	v_cndmask_b32_e64 v71, 1.0, v81, s[56:57]
	v_mul_f32_e32 v67, v67, v69
	v_cndmask_b32_e64 v69, 1.0, v69, s[52:53]
	v_mul_f32_e32 v80, v71, v80
	v_mul_f32_e32 v68, v68, v65
	v_cndmask_b32_e64 v65, 1.0, v65, s[50:51]
	v_mul_f32_e32 v69, v69, v80
	v_cndmask_b32_e64 v68, 0, v68, s[50:51]
	v_cndmask_b32_e64 v67, 0, v67, s[52:53]
	v_mul_f32_e32 v65, v65, v69
	v_mov_b32_e32 v66, v64
	v_mul_f32_e32 v174, v68, v69
	v_mul_f32_e32 v175, v67, v80
	v_mov_b32_e32 v67, v65
	v_permlane32_swap_b32_e32 v64, v66
	v_permlane32_swap_b32_e32 v65, v67
	v_min_f32_e32 v69, 0x42a00000, v75
	v_pk_mul_f32 v[176:177], v[64:65], v[66:67]
	v_min_f32_e32 v68, 0x42a00000, v74
	v_exp_f32_e32 v69, v69
	v_min_f32_e32 v65, 0x42a00000, v73
	v_exp_f32_e32 v68, v68
	v_min_f32_e32 v64, 0x42a00000, v72
	v_exp_f32_e32 v65, v65
	v_cndmask_b32_e64 v70, 0, v70, s[54:55]
	v_exp_f32_e32 v64, v64
	v_mul_f32_e32 v172, v71, v70
	v_add_f32_e32 v71, 1.0, v69
	v_add_f32_e32 v70, 1.0, v68
	v_rcp_f32_e32 v71, v71
	v_cndmask_b32_e64 v239, 1.0, v67, s[4:5]
	v_add_f32_e32 v67, 1.0, v65
	v_rcp_f32_e32 v70, v70
	v_cndmask_b32_e64 v238, 1.0, v66, s[4:5]
	v_add_f32_e32 v66, 1.0, v64
	v_rcp_f32_e32 v67, v67
	v_rcp_f32_e32 v66, v66
	v_mul_f32_e32 v69, v69, v71
	v_mul_f32_e32 v68, v68, v70
	v_cndmask_b32_e64 v70, 1.0, v70, s[62:63]
	v_cndmask_b32_e64 v179, 0, v69, s[64:65]
	v_cndmask_b32_e64 v69, 1.0, v71, s[64:65]
	v_mul_f32_e32 v65, v65, v67
	v_cndmask_b32_e64 v67, 1.0, v67, s[60:61]
	v_mul_f32_e32 v70, v69, v70
	v_mul_f32_e32 v64, v64, v66
	v_cndmask_b32_e64 v66, 1.0, v66, s[58:59]
	v_mul_f32_e32 v67, v67, v70
	v_cndmask_b32_e64 v64, 0, v64, s[58:59]
	v_cndmask_b32_e64 v68, 0, v68, s[62:63]
	v_mul_f32_e32 v66, v66, v67
	v_mul_f32_e32 v180, v64, v67
	v_mul_f32_e32 v178, v69, v68
	v_mov_b32_e32 v64, v66
	s_nop 0
	v_permlane32_swap_b32_e32 v66, v64
	v_min_f32_e32 v69, 0x42a00000, v79
	v_cndmask_b32_e64 v65, 0, v65, s[60:61]
	v_mul_f32_e32 v240, v66, v64
	v_min_f32_e32 v68, 0x42a00000, v78
	v_exp_f32_e32 v69, v69
	v_mul_f32_e32 v181, v65, v70
	v_min_f32_e32 v66, 0x42a00000, v77
	v_exp_f32_e32 v68, v68
	v_min_f32_e32 v65, 0x42a00000, v76
	v_exp_f32_e32 v66, v66
	v_exp_f32_e32 v65, v65
	v_add_f32_e32 v71, 1.0, v69
	v_add_f32_e32 v70, 1.0, v68
	v_rcp_f32_e32 v71, v71
	v_cndmask_b32_e64 v241, 1.0, v64, s[4:5]
	v_add_f32_e32 v64, 1.0, v66
	v_rcp_f32_e32 v70, v70
	v_add_f32_e32 v67, 1.0, v65
	v_rcp_f32_e32 v64, v64
	v_rcp_f32_e32 v67, v67
	v_mul_f32_e32 v69, v69, v71
	v_mul_f32_e32 v68, v68, v70
	v_cndmask_b32_e64 v70, 1.0, v70, s[70:71]
	v_cndmask_b32_e64 v183, 0, v69, s[72:73]
	v_cndmask_b32_e64 v69, 1.0, v71, s[72:73]
	v_mul_f32_e32 v66, v66, v64
	v_cndmask_b32_e64 v64, 1.0, v64, s[68:69]
	v_mul_f32_e32 v70, v69, v70
	v_mul_f32_e32 v65, v65, v67
	v_cndmask_b32_e64 v67, 1.0, v67, s[66:67]
	v_mul_f32_e32 v64, v64, v70
	v_mul_f32_e32 v242, v67, v64
	v_cndmask_b32_e64 v84, 0, v84, s[36:37]
	v_cndmask_b32_e64 v86, 0, v86, s[38:39]
	v_mul_f32_e32 v83, v87, v89
	v_cndmask_b32_e64 v65, 0, v65, s[66:67]
	v_cndmask_b32_e64 v66, 0, v66, s[68:69]
	v_cndmask_b32_e64 v68, 0, v68, s[70:71]
	v_mov_b32_e32 v243, v242
	v_mul_f32_e32 v163, v88, v84
	v_mul_f32_e32 v164, v90, v86
	v_cndmask_b32_e64 v165, 0, v83, s[40:41]
	v_mul_f32_e32 v184, v65, v64
	v_mul_f32_e32 v185, v66, v70
	v_mul_f32_e32 v182, v69, v68
	v_permlane32_swap_b32_e32 v242, v243
